# phase0: hand-written weight transposes (34 loads in flight per item) + pipelined adaLN; phase1: even WGs run norm before fold
# speedup vs baseline: 1.0108x; 1.0011x over previous
.LBB0_28:
	s_cmpk_gt_i32 s90, 0x157f
	s_cbranch_scc1 .LBB0_84
	s_waitcnt lgkmcnt(0)
	s_lshl_b32 s30, s92, 14
	v_lshrrev_b32_e32 v0, 5, v180
	v_and_b32_e32 v9, 31, v180
	v_lshlrev_b32_e32 v10, 2, v9
	v_lshl_add_u32 v1, v0, 13, v10
	v_lshl_add_u32 v2, v0, 12, v10
	v_mul_u32_u24_e32 v3, 0x2c00, v0
	v_add_u32_e32 v3, v3, v10
	v_mul_u32_u24_e32 v4, 0x84, v0
	v_add3_u32 v4, v4, v10, s30
	v_and_b32_e32 v11, 7, v180
	v_lshrrev_b32_e32 v12, 3, v180
	v_mul_u32_u24_e32 v5, 0x420, v11
	v_lshl_add_u32 v5, v12, 2, v5
	v_add_u32_e32 v5, s30, v5
	v_lshlrev_b32_e32 v13, 4, v11
	v_lshl_add_u32 v6, v12, 11, v13
	v_mul_u32_u24_e32 v7, 0x1600, v12
	v_add_u32_e32 v7, v7, v13
	v_lshlrev_b32_e32 v8, 5, v11
	s_mov_b32 s16, s90
.Ltr_loop:
	s_mov_b32 s9, 0
	s_mov_b64 s[10:11], s[48:49]
	s_cmpk_lt_u32 s16, 0x200
	s_cbranch_scc0 .Ltr_k1
	s_lshr_b32 s0, s16, 5
	s_and_b32 s1, s16, 31
	s_lshl_b32 s2, s0, 19
	s_lshl_b32 s3, s1, 7
	s_add_i32 s2, s2, s3
	s_add_i32 s2, s2, 0x800
	s_add_u32 s2, s2, s70
	s_addc_u32 s3, s71, 0
	s_mov_b32 s17, 0x4000
	v_mov_b32_e32 v14, v1
	s_lshr_b32 s18, s1, 3
	s_lshl_b32 s18, s18, 8
	s_and_b32 s6, s1, 1
	s_lshl_b32 s6, s6, 7
	s_add_i32 s18, s18, s6
	s_bfe_u32 s6, s1, 0x20001
	s_lshl_b32 s6, s6, 5
	s_add_i32 s18, s18, s6
	s_lshl_b32 s18, s18, 11
	s_lshl_b32 s6, s0, 7
	s_add_i32 s6, s6, s18
	s_add_i32 s6, s6, 0x400000
	s_add_u32 s6, s6, s80
	s_addc_u32 s7, s81, 0
	s_mov_b32 s8, 0x4000
	v_mov_b32_e32 v15, v6
	s_branch .Ltr_go
.Ltr_k1:
	s_cmpk_lt_u32 s16, 0x300
	s_cbranch_scc0 .Ltr_k2
	s_sub_i32 s1, s16, 0x200
	s_lshr_b32 s0, s1, 4
	s_and_b32 s1, s1, 15
	s_lshl_b32 s2, s0, 19
	s_lshl_b32 s3, s1, 7
	s_add_i32 s2, s2, s3
	s_add_i32 s2, s2, 0x1800
	s_add_u32 s2, s2, s70
	s_addc_u32 s3, s71, 0
	s_mov_b32 s17, 0x4000
	v_mov_b32_e32 v14, v1
	s_lshl_b32 s18, s1, 5
	s_add_i32 s18, s18, 0x400
	s_lshl_b32 s18, s18, 11
	s_lshl_b32 s6, s0, 7
	s_add_i32 s6, s6, s18
	s_add_i32 s6, s6, 0x600000
	s_add_u32 s6, s6, s80
	s_addc_u32 s7, s81, 0
	s_mov_b32 s8, 0x4000
	v_mov_b32_e32 v15, v6
	s_branch .Ltr_go
.Ltr_k2:
	s_cmpk_lt_u32 s16, 0x500
	s_cbranch_scc0 .Ltr_k3
	s_sub_i32 s1, s16, 0x300
	s_lshr_b32 s0, s1, 5
	s_and_b32 s1, s1, 31
	s_lshl_b32 s2, s0, 18
	s_lshl_b32 s3, s1, 7
	s_add_i32 s2, s2, s3
	s_add_u32 s2, s2, s52
	s_addc_u32 s3, s53, 0
	s_mov_b32 s17, 0x2000
	v_mov_b32_e32 v14, v2
	s_lshl_b32 s18, s1, 16
	s_lshl_b32 s6, s0, 7
	s_add_i32 s6, s6, s18
	s_add_i32 s6, s6, 0xa00000
	s_add_u32 s6, s6, s80
	s_addc_u32 s7, s81, 0
	s_mov_b32 s8, 0x4000
	v_mov_b32_e32 v15, v6
	s_mov_b32 s9, 1
	s_lshl_b32 s12, s0, 8
	s_cmp_lt_u32 s0, 8
	s_cbranch_scc0 .Ltr_ks1
	s_add_u32 s10, s48, s12
	s_addc_u32 s11, s49, 0
	s_branch .Ltr_go
.Ltr_ks1:
	s_sub_i32 s12, s12, 0x800
	s_add_u32 s10, s50, s12
	s_addc_u32 s11, s51, 0
	s_branch .Ltr_go
.Ltr_k3:
	s_cmpk_lt_u32 s16, 0x1000
	s_cbranch_scc0 .Ltr_k5
	s_cmpk_lt_u32 s16, 0xa80
	s_cbranch_scc0 .Ltr_k4
	s_sub_i32 s1, s16, 0x500
	s_mov_b64 s[12:13], s[72:73]
	s_mov_b32 s14, 0
	s_branch .Ltr_gu
.Ltr_k4:
	s_sub_i32 s1, s16, 0xa80
	s_mov_b64 s[12:13], s[74:75]
	s_mov_b32 s14, 128
.Ltr_gu:
	s_mul_hi_u32 s0, s1, 0x2e8ba2f
	s_mul_i32 s2, s0, 88
	s_sub_i32 s1, s1, s2
	s_mul_i32 s2, s0, 0xb0000
	s_lshl_b32 s3, s1, 7
	s_add_i32 s2, s2, s3
	s_add_u32 s2, s2, s12
	s_addc_u32 s3, s13, 0
	s_mov_b32 s17, 0x5800
	v_mov_b32_e32 v14, v3
	s_lshr_b32 s18, s1, 2
	s_lshl_b32 s18, s18, 8
	s_and_b32 s6, s1, 3
	s_lshl_b32 s6, s6, 5
	s_add_i32 s18, s18, s6
	s_add_i32 s18, s18, s14
	s_lshl_b32 s18, s18, 11
	s_lshl_b32 s6, s0, 7
	s_add_i32 s6, s6, s18
	s_add_i32 s6, s6, 0xc00000
	s_add_u32 s6, s6, s80
	s_addc_u32 s7, s81, 0
	s_mov_b32 s8, 0x4000
	v_mov_b32_e32 v15, v6
	s_branch .Ltr_go
.Ltr_k5:
	s_sub_i32 s1, s16, 0x1000
	s_lshr_b32 s0, s1, 5
	s_and_b32 s1, s1, 31
	s_lshl_b32 s2, s0, 18
	s_lshl_b32 s3, s1, 7
	s_add_i32 s2, s2, s3
	s_add_u32 s2, s2, s76
	s_addc_u32 s3, s77, 0
	s_mov_b32 s17, 0x2000
	v_mov_b32_e32 v14, v2
	s_mul_i32 s18, s1, 0x2c000
	s_lshl_b32 s6, s0, 7
	s_add_i32 s6, s6, s18
	s_add_i32 s6, s6, 0x1800000
	s_add_u32 s6, s6, s80
	s_addc_u32 s7, s81, 0
	s_mov_b32 s8, 0xb000
	v_mov_b32_e32 v15, v7
.Ltr_go:
	global_load_dwordx4 v[126:129], v8, s[10:11]
	global_load_dwordx4 v[130:133], v8, s[10:11] offset:16
	global_load_dword v93, v14, s[2:3]
	s_add_u32 s2, s2, s17
	s_addc_u32 s3, s3, 0
	global_load_dword v94, v14, s[2:3]
	s_add_u32 s2, s2, s17
	s_addc_u32 s3, s3, 0
	global_load_dword v95, v14, s[2:3]
	s_add_u32 s2, s2, s17
	s_addc_u32 s3, s3, 0
	global_load_dword v96, v14, s[2:3]
	s_add_u32 s2, s2, s17
	s_addc_u32 s3, s3, 0
	global_load_dword v97, v14, s[2:3]
	s_add_u32 s2, s2, s17
	s_addc_u32 s3, s3, 0
	global_load_dword v98, v14, s[2:3]
	s_add_u32 s2, s2, s17
	s_addc_u32 s3, s3, 0
	global_load_dword v99, v14, s[2:3]
	s_add_u32 s2, s2, s17
	s_addc_u32 s3, s3, 0
	global_load_dword v100, v14, s[2:3]
	s_add_u32 s2, s2, s17
	s_addc_u32 s3, s3, 0
	global_load_dword v101, v14, s[2:3]
	s_add_u32 s2, s2, s17
	s_addc_u32 s3, s3, 0
	global_load_dword v102, v14, s[2:3]
	s_add_u32 s2, s2, s17
	s_addc_u32 s3, s3, 0
	global_load_dword v103, v14, s[2:3]
	s_add_u32 s2, s2, s17
	s_addc_u32 s3, s3, 0
	global_load_dword v104, v14, s[2:3]
	s_add_u32 s2, s2, s17
	s_addc_u32 s3, s3, 0
	global_load_dword v105, v14, s[2:3]
	s_add_u32 s2, s2, s17
	s_addc_u32 s3, s3, 0
	global_load_dword v106, v14, s[2:3]
	s_add_u32 s2, s2, s17
	s_addc_u32 s3, s3, 0
	global_load_dword v107, v14, s[2:3]
	s_add_u32 s2, s2, s17
	s_addc_u32 s3, s3, 0
	global_load_dword v108, v14, s[2:3]
	s_add_u32 s2, s2, s17
	s_addc_u32 s3, s3, 0
	global_load_dword v109, v14, s[2:3]
	s_add_u32 s2, s2, s17
	s_addc_u32 s3, s3, 0
	global_load_dword v110, v14, s[2:3]
	s_add_u32 s2, s2, s17
	s_addc_u32 s3, s3, 0
	global_load_dword v111, v14, s[2:3]
	s_add_u32 s2, s2, s17
	s_addc_u32 s3, s3, 0
	global_load_dword v112, v14, s[2:3]
	s_add_u32 s2, s2, s17
	s_addc_u32 s3, s3, 0
	global_load_dword v113, v14, s[2:3]
	s_add_u32 s2, s2, s17
	s_addc_u32 s3, s3, 0
	global_load_dword v114, v14, s[2:3]
	s_add_u32 s2, s2, s17
	s_addc_u32 s3, s3, 0
	global_load_dword v115, v14, s[2:3]
	s_add_u32 s2, s2, s17
	s_addc_u32 s3, s3, 0
	global_load_dword v116, v14, s[2:3]
	s_add_u32 s2, s2, s17
	s_addc_u32 s3, s3, 0
	global_load_dword v117, v14, s[2:3]
	s_add_u32 s2, s2, s17
	s_addc_u32 s3, s3, 0
	global_load_dword v118, v14, s[2:3]
	s_add_u32 s2, s2, s17
	s_addc_u32 s3, s3, 0
	global_load_dword v119, v14, s[2:3]
	s_add_u32 s2, s2, s17
	s_addc_u32 s3, s3, 0
	global_load_dword v120, v14, s[2:3]
	s_add_u32 s2, s2, s17
	s_addc_u32 s3, s3, 0
	global_load_dword v121, v14, s[2:3]
	s_add_u32 s2, s2, s17
	s_addc_u32 s3, s3, 0
	global_load_dword v122, v14, s[2:3]
	s_add_u32 s2, s2, s17
	s_addc_u32 s3, s3, 0
	global_load_dword v123, v14, s[2:3]
	s_add_u32 s2, s2, s17
	s_addc_u32 s3, s3, 0
	global_load_dword v124, v14, s[2:3]
	s_waitcnt vmcnt(0)
	ds_write_b32 v4, v93
	ds_write_b32 v4, v94 offset:264
	ds_write_b32 v4, v95 offset:528
	ds_write_b32 v4, v96 offset:792
	ds_write_b32 v4, v97 offset:1056
	ds_write_b32 v4, v98 offset:1320
	ds_write_b32 v4, v99 offset:1584
	ds_write_b32 v4, v100 offset:1848
	ds_write_b32 v4, v101 offset:2112
	ds_write_b32 v4, v102 offset:2376
	ds_write_b32 v4, v103 offset:2640
	ds_write_b32 v4, v104 offset:2904
	ds_write_b32 v4, v105 offset:3168
	ds_write_b32 v4, v106 offset:3432
	ds_write_b32 v4, v107 offset:3696
	ds_write_b32 v4, v108 offset:3960
	ds_write_b32 v4, v109 offset:4224
	ds_write_b32 v4, v110 offset:4488
	ds_write_b32 v4, v111 offset:4752
	ds_write_b32 v4, v112 offset:5016
	ds_write_b32 v4, v113 offset:5280
	ds_write_b32 v4, v114 offset:5544
	ds_write_b32 v4, v115 offset:5808
	ds_write_b32 v4, v116 offset:6072
	ds_write_b32 v4, v117 offset:6336
	ds_write_b32 v4, v118 offset:6600
	ds_write_b32 v4, v119 offset:6864
	ds_write_b32 v4, v120 offset:7128
	ds_write_b32 v4, v121 offset:7392
	ds_write_b32 v4, v122 offset:7656
	ds_write_b32 v4, v123 offset:7920
	ds_write_b32 v4, v124 offset:8184
	ds_read2_b32 v[32:33], v5 offset0:0 offset1:33
	ds_read2_b32 v[34:35], v5 offset0:66 offset1:99
	ds_read2_b32 v[36:37], v5 offset0:132 offset1:165
	ds_read2_b32 v[38:39], v5 offset0:198 offset1:231
	ds_read2_b32 v[40:41], v5 offset0:8 offset1:41
	ds_read2_b32 v[42:43], v5 offset0:74 offset1:107
	ds_read2_b32 v[44:45], v5 offset0:140 offset1:173
	ds_read2_b32 v[46:47], v5 offset0:206 offset1:239
	ds_read2_b32 v[48:49], v5 offset0:16 offset1:49
	ds_read2_b32 v[50:51], v5 offset0:82 offset1:115
	ds_read2_b32 v[52:53], v5 offset0:148 offset1:181
	ds_read2_b32 v[54:55], v5 offset0:214 offset1:247
	ds_read2_b32 v[56:57], v5 offset0:24 offset1:57
	ds_read2_b32 v[58:59], v5 offset0:90 offset1:123
	ds_read2_b32 v[60:61], v5 offset0:156 offset1:189
	ds_read2_b32 v[62:63], v5 offset0:222 offset1:255
	s_waitcnt lgkmcnt(0)
	s_cmp_eq_u32 s9, 0
	s_cbranch_scc1 .Ltr_nomul
	v_mul_f32_e32 v32, v32, v126
	v_mul_f32_e32 v33, v33, v127
	v_mul_f32_e32 v34, v34, v128
	v_mul_f32_e32 v35, v35, v129
	v_mul_f32_e32 v36, v36, v130
	v_mul_f32_e32 v37, v37, v131
	v_mul_f32_e32 v38, v38, v132
	v_mul_f32_e32 v39, v39, v133
	v_mul_f32_e32 v40, v40, v126
	v_mul_f32_e32 v41, v41, v127
	v_mul_f32_e32 v42, v42, v128
	v_mul_f32_e32 v43, v43, v129
	v_mul_f32_e32 v44, v44, v130
	v_mul_f32_e32 v45, v45, v131
	v_mul_f32_e32 v46, v46, v132
	v_mul_f32_e32 v47, v47, v133
	v_mul_f32_e32 v48, v48, v126
	v_mul_f32_e32 v49, v49, v127
	v_mul_f32_e32 v50, v50, v128
	v_mul_f32_e32 v51, v51, v129
	v_mul_f32_e32 v52, v52, v130
	v_mul_f32_e32 v53, v53, v131
	v_mul_f32_e32 v54, v54, v132
	v_mul_f32_e32 v55, v55, v133
	v_mul_f32_e32 v56, v56, v126
	v_mul_f32_e32 v57, v57, v127
	v_mul_f32_e32 v58, v58, v128
	v_mul_f32_e32 v59, v59, v129
	v_mul_f32_e32 v60, v60, v130
	v_mul_f32_e32 v61, v61, v131
	v_mul_f32_e32 v62, v62, v132
	v_mul_f32_e32 v63, v63, v133
.Ltr_nomul:
	v_cvt_pk_bf16_f32 v64, v32, v33
	v_cvt_pk_bf16_f32 v65, v34, v35
	v_cvt_pk_bf16_f32 v66, v36, v37
	v_cvt_pk_bf16_f32 v67, v38, v39
	global_store_dwordx4 v15, v[64:67], s[6:7]
	s_add_u32 s6, s6, s8
	s_addc_u32 s7, s7, 0
	v_cvt_pk_bf16_f32 v68, v40, v41
	v_cvt_pk_bf16_f32 v69, v42, v43
	v_cvt_pk_bf16_f32 v70, v44, v45
	v_cvt_pk_bf16_f32 v71, v46, v47
	global_store_dwordx4 v15, v[68:71], s[6:7]
	s_add_u32 s6, s6, s8
	s_addc_u32 s7, s7, 0
	v_cvt_pk_bf16_f32 v72, v48, v49
	v_cvt_pk_bf16_f32 v73, v50, v51
	v_cvt_pk_bf16_f32 v74, v52, v53
	v_cvt_pk_bf16_f32 v75, v54, v55
	global_store_dwordx4 v15, v[72:75], s[6:7]
	s_add_u32 s6, s6, s8
	s_addc_u32 s7, s7, 0
	v_cvt_pk_bf16_f32 v76, v56, v57
	v_cvt_pk_bf16_f32 v77, v58, v59
	v_cvt_pk_bf16_f32 v78, v60, v61
	v_cvt_pk_bf16_f32 v79, v62, v63
	global_store_dwordx4 v15, v[76:79], s[6:7]
	s_add_i32 s16, s16, s91
	s_cmpk_gt_i32 s16, 0x157f
	s_cbranch_scc0 .Ltr_loop

.LBB0_172:
	s_cmp_lt_i32 s82, 2
	s_cselect_b64 s[2:3], -1, 0
	s_and_b64 s[6:7], s[2:3], s[0:1]
	s_andn2_b64 vcc, exec, s[6:7]
	s_cbranch_vccnz .LBB0_197
	s_bitcmp1_b32 s33, 0
	s_cbranch_scc0 .LBB0_188
.Lp1_fold:
	s_cmpk_gt_i32 s33, 0xff
	s_cbranch_scc1 .LBB0_188
	v_lshrrev_b32_e32 v0, 9, v164
	v_sub_u32_e32 v2, 32, v0
	v_sub_u32_e32 v0, 30, v0
	v_or_b32_e32 v5, 0x400, v164
	v_lshrrev_b32_e32 v0, 1, v0
	v_lshrrev_b32_e32 v21, 7, v5
	v_add_u32_e32 v5, 0x600, v164
	v_add_u32_e32 v0, 1, v0
	v_lshrrev_b32_e32 v22, 7, v5
	v_or_b32_e32 v5, 0x800, v164
	v_lshrrev_b32_e32 v23, 7, v5
	v_add_u32_e32 v5, 0xa00, v164
	v_and_b32_e32 v6, 7, v0
	v_lshlrev_b32_e32 v0, 1, v0
	v_lshlrev_b32_e32 v3, 2, v164
	v_lshrrev_b32_e32 v24, 7, v5
	v_or_b32_e32 v5, 0xc00, v164
	s_movk_i32 s2, 0xe00
	v_and_b32_e32 v28, 48, v0
	v_lshlrev_b32_e32 v0, 11, v2
	s_mov_b32 s10, 0x1f000
	v_lshrrev_b32_e32 v25, 7, v5
	v_cmp_gt_u32_e32 vcc, s2, v5
	v_add_u32_e32 v5, 0xe00, v164
	v_and_or_b32 v0, v0, s10, v3
	v_lshrrev_b32_e32 v26, 7, v5
	v_and_b32_e32 v5, 62, v2
	v_add_u32_e32 v0, 0, v0
	s_add_u32 s20, s80, 0x180000
	v_add_u32_e32 v30, 0x4000, v0
	v_lshl_or_b32 v0, v5, 9, v164
	s_addc_u32 s21, s81, 0
	v_and_b32_e32 v16, 0x7f, v164
	v_lshrrev_b32_e32 v17, 7, v164
	v_mov_b32_e32 v1, 0
	v_add_u32_e32 v31, 0xfffffe00, v0
	v_lshlrev_b32_e32 v0, 2, v0
	s_mov_b64 s[0:1], 0x180000
	s_add_u32 s8, s80, 0x600000
	v_lshlrev_b32_e32 v4, 3, v17
	v_add_u32_e32 v19, 0, v3
	v_add_u32_e32 v165, 0x200, v164
	v_cmp_ne_u32_e64 s[4:5], v2, v5
	v_lshl_add_u64 v[2:3], s[80:81], 0, v[0:1]
	v_lshl_add_u32 v0, v16, 2, 0
	s_addc_u32 s9, s81, 0
	s_mov_b32 s11, 0
	v_lshl_add_u32 v18, v17, 12, 0
	v_lshrrev_b32_e32 v20, 7, v165
	v_cmp_ne_u32_e64 s[2:3], 0, v6
	v_add_u32_e32 v27, 0x4000, v19
	v_lshlrev_b32_e32 v29, 12, v6
	v_lshl_add_u64 v[2:3], v[2:3], 0, s[0:1]
	v_add_u32_e32 v32, 0x4000, v0
	s_mov_b64 s[12:13], 0x800
	s_movk_i32 s22, 0x3dff
	v_lshlrev_b32_e32 v4, 1, v4
	s_mov_b32 s23, s33

.LBB0_186:
	v_add_u32_e32 v5, s0, v18
	ds_read2st64_b32 v[14:15], v0 offset1:2
	ds_read2st64_b32 v[98:99], v0 offset0:4 offset1:6
	ds_read2st64_b32 v[100:101], v0 offset0:8 offset1:10
	ds_read2st64_b32 v[102:103], v0 offset0:12 offset1:14
	ds_read_b128 v[34:37], v5
	ds_read_b128 v[38:41], v5 offset:16
	ds_read_b128 v[42:45], v5 offset:512
	ds_read_b128 v[46:49], v5 offset:528
	ds_read_b128 v[50:53], v5 offset:1024
	ds_read_b128 v[54:57], v5 offset:1040
	ds_read_b128 v[58:61], v5 offset:1536
	ds_read_b128 v[62:65], v5 offset:1552
	ds_read_b128 v[66:69], v5 offset:2048
	ds_read_b128 v[70:73], v5 offset:2064
	ds_read_b128 v[74:77], v5 offset:2560
	ds_read_b128 v[78:81], v5 offset:2576
	ds_read_b128 v[82:85], v5 offset:3072
	ds_read_b128 v[86:89], v5 offset:3088
	ds_read_b128 v[90:93], v5 offset:3584
	ds_read_b128 v[94:97], v5 offset:3600
	s_waitcnt lgkmcnt(14)
	v_mov_b32_e32 v112, v34
	s_waitcnt lgkmcnt(13)
	v_mov_b32_e32 v113, v42
	v_mov_b32_e32 v42, v35
	v_mov_b32_e32 v34, v36
	v_mov_b32_e32 v35, v44
	v_mov_b32_e32 v44, v37
	s_waitcnt lgkmcnt(11)
	v_mov_b32_e32 v36, v50
	s_waitcnt lgkmcnt(9)
	v_mov_b32_e32 v37, v58
	v_mov_b32_e32 v58, v51
	v_mov_b32_e32 v50, v52
	v_mov_b32_e32 v51, v60
	v_mov_b32_e32 v60, v53
	s_waitcnt lgkmcnt(7)
	v_mov_b32_e32 v52, v66
	s_waitcnt lgkmcnt(5)
	v_mov_b32_e32 v53, v74
	v_mov_b32_e32 v74, v67
	v_mov_b32_e32 v66, v68
	v_mov_b32_e32 v67, v76
	v_mov_b32_e32 v76, v69
	s_waitcnt lgkmcnt(3)
	v_mov_b32_e32 v68, v82
	s_waitcnt lgkmcnt(1)
	v_mov_b32_e32 v69, v90
	v_mov_b32_e32 v104, v15
	v_mov_b32_e32 v90, v83
	v_pk_fma_f32 v[12:13], v[14:15], v[112:113], v[12:13] op_sel_hi:[0,1,1]
	v_pk_fma_f32 v[10:11], v[14:15], v[36:37], v[10:11] op_sel_hi:[0,1,1]
	v_pk_fma_f32 v[8:9], v[14:15], v[52:53], v[8:9] op_sel_hi:[0,1,1]
	v_pk_fma_f32 v[6:7], v[14:15], v[68:69], v[6:7] op_sel_hi:[0,1,1]
	v_mov_b32_e32 v82, v84
	v_mov_b32_e32 v83, v92
	v_pk_fma_f32 v[12:13], v[104:105], v[42:43], v[12:13] op_sel_hi:[0,1,1]
	v_pk_fma_f32 v[10:11], v[104:105], v[58:59], v[10:11] op_sel_hi:[0,1,1]
	v_pk_fma_f32 v[8:9], v[104:105], v[74:75], v[8:9] op_sel_hi:[0,1,1]
	v_pk_fma_f32 v[6:7], v[104:105], v[90:91], v[6:7] op_sel_hi:[0,1,1]
	v_mov_b32_e32 v106, v99
	v_mov_b32_e32 v92, v85
	v_pk_fma_f32 v[12:13], v[98:99], v[34:35], v[12:13] op_sel_hi:[0,1,1]
	v_pk_fma_f32 v[10:11], v[98:99], v[50:51], v[10:11] op_sel_hi:[0,1,1]
	v_pk_fma_f32 v[8:9], v[98:99], v[66:67], v[8:9] op_sel_hi:[0,1,1]
	v_pk_fma_f32 v[6:7], v[98:99], v[82:83], v[6:7] op_sel_hi:[0,1,1]
	v_mov_b32_e32 v84, v38
	v_mov_b32_e32 v85, v46
	v_mov_b32_e32 v46, v39
	v_mov_b32_e32 v38, v40
	v_mov_b32_e32 v39, v48
	v_mov_b32_e32 v48, v41
	v_mov_b32_e32 v40, v54
	v_mov_b32_e32 v41, v62
	v_mov_b32_e32 v62, v55
	v_mov_b32_e32 v54, v56
	v_mov_b32_e32 v55, v64
	v_mov_b32_e32 v64, v57
	v_mov_b32_e32 v56, v70
	v_mov_b32_e32 v57, v78
	v_mov_b32_e32 v78, v71
	v_mov_b32_e32 v70, v72
	v_mov_b32_e32 v71, v80
	v_mov_b32_e32 v80, v73
	v_mov_b32_e32 v72, v86
	s_waitcnt lgkmcnt(0)
	v_mov_b32_e32 v73, v94
	v_pk_fma_f32 v[12:13], v[106:107], v[44:45], v[12:13] op_sel_hi:[0,1,1]
	v_pk_fma_f32 v[10:11], v[106:107], v[60:61], v[10:11] op_sel_hi:[0,1,1]
	v_pk_fma_f32 v[8:9], v[106:107], v[76:77], v[8:9] op_sel_hi:[0,1,1]
	v_pk_fma_f32 v[6:7], v[106:107], v[92:93], v[6:7] op_sel_hi:[0,1,1]
	v_mov_b32_e32 v108, v101
	v_mov_b32_e32 v94, v87
	v_pk_fma_f32 v[12:13], v[100:101], v[84:85], v[12:13] op_sel_hi:[0,1,1]
	v_pk_fma_f32 v[10:11], v[100:101], v[40:41], v[10:11] op_sel_hi:[0,1,1]
	v_pk_fma_f32 v[8:9], v[100:101], v[56:57], v[8:9] op_sel_hi:[0,1,1]
	v_pk_fma_f32 v[6:7], v[100:101], v[72:73], v[6:7] op_sel_hi:[0,1,1]
	v_mov_b32_e32 v86, v88
	v_mov_b32_e32 v87, v96
	v_pk_fma_f32 v[12:13], v[108:109], v[46:47], v[12:13] op_sel_hi:[0,1,1]
	v_pk_fma_f32 v[10:11], v[108:109], v[62:63], v[10:11] op_sel_hi:[0,1,1]
	v_pk_fma_f32 v[8:9], v[108:109], v[78:79], v[8:9] op_sel_hi:[0,1,1]
	v_pk_fma_f32 v[6:7], v[108:109], v[94:95], v[6:7] op_sel_hi:[0,1,1]
	s_add_i32 s0, s0, 32
	v_mov_b32_e32 v110, v103
	v_mov_b32_e32 v96, v89
	v_pk_fma_f32 v[12:13], v[102:103], v[38:39], v[12:13] op_sel_hi:[0,1,1]
	v_pk_fma_f32 v[10:11], v[102:103], v[54:55], v[10:11] op_sel_hi:[0,1,1]
	v_pk_fma_f32 v[8:9], v[102:103], v[70:71], v[8:9] op_sel_hi:[0,1,1]
	v_pk_fma_f32 v[6:7], v[102:103], v[86:87], v[6:7] op_sel_hi:[0,1,1]
	v_add_u32_e32 v0, 0x1000, v0
	s_cmpk_eq_i32 s0, 0x200
	v_pk_fma_f32 v[12:13], v[110:111], v[48:49], v[12:13] op_sel_hi:[0,1,1]
	v_pk_fma_f32 v[10:11], v[110:111], v[64:65], v[10:11] op_sel_hi:[0,1,1]
	v_pk_fma_f32 v[8:9], v[110:111], v[80:81], v[8:9] op_sel_hi:[0,1,1]
	v_pk_fma_f32 v[6:7], v[110:111], v[96:97], v[6:7] op_sel_hi:[0,1,1]
	s_cbranch_scc0 .LBB0_186
	s_lshl_b32 s0, s25, 9
	s_or_b32 s0, s24, s0
	v_cvt_pk_bf16_f32 v12, v12, v13
	v_cvt_pk_bf16_f32 v13, v10, v11
	v_cvt_pk_bf16_f32 v14, v8, v9
	v_cvt_pk_bf16_f32 v15, v6, v7
	v_or_b32_e32 v6, s0, v16
	v_ashrrev_i32_e32 v7, 31, v6
	v_lshlrev_b64 v[6:7], 11, v[6:7]
	v_lshl_add_u64 v[6:7], s[8:9], 0, v[6:7]
	s_lshl_b32 s10, s10, 1
	v_lshl_add_u64 v[6:7], v[6:7], 0, s[10:11]
	v_mov_b32_e32 v5, v1
	s_add_i32 s23, s23, s84
	v_lshl_add_u64 v[6:7], v[6:7], 0, v[4:5]
	s_cmpk_gt_i32 s23, 0xff
	global_store_dwordx4 v[6:7], v[12:15], off
	s_barrier
	s_cbranch_scc0 .LBB0_175
	s_bitcmp1_b32 s33, 0
	s_cbranch_scc0 .LBB0_197

.Lp1_after_norm:
	s_bitcmp1_b32 s33, 0
	s_cbranch_scc1 .LBB0_197
	s_waitcnt vmcnt(0) lgkmcnt(0)
	s_branch .Lp1_fold
